# fused p13+p14: partials via write-through sc0sc1 stores/loads, no per-WG L2 writeback/invalidate, single polling wave
# speedup vs baseline: 1.0214x; 1.0214x over previous
.LBB0_63:
	s_or_b64 exec, exec, s[8:9]
	v_lshlrev_b32_e32 v96, 6, v147
	v_lshl_add_u32 v96, v145, 4, v96
	v_lshl_add_u32 v96, v146, 2, v96
	v_lshlrev_b32_e32 v97, 2, v147
	s_ashr_i32 s0, s6, 13
	s_mulk_i32 s0, 0x1800
	s_ashr_i32 s1, s0, 31
	s_lshl_b64 s[0:1], s[0:1], 2
	s_add_u32 s0, s18, s0
	s_addc_u32 s1, s19, s1
	v_lshlrev_b32_e32 v20, 5, v145
	v_lshlrev_b32_e32 v21, 2, v146
	v_or3_b32 v20, v20, v21, s4
	v_lshlrev_b32_e32 v30, 2, v20
	v_add_u32_e32 v21, s6, v147
	v_lshl_add_u32 v31, v21, 12, v30
	global_load_dwordx4 v[26:29], v30, s[0:1]
	global_load_dwordx4 v[138:141], v30, s[0:1] offset:64
	global_load_dwordx4 v[142:145], v30, s[0:1] offset:512
	global_load_dwordx4 v[146:149], v30, s[0:1] offset:576
	v_mov_b32_e32 v20, v31
	global_load_dwordx4 v[150:153], v20, s[58:59]
	global_load_dwordx4 v[154:157], v20, s[58:59] offset:64
	global_load_dwordx4 v[164:167], v20, s[58:59] offset:512
	global_load_dwordx4 v[168:171], v20, s[58:59] offset:576
	v_add_u32_e32 v20, 0x10000, v31
	global_load_dwordx4 v[172:175], v20, s[58:59]
	global_load_dwordx4 v[198:201], v20, s[58:59] offset:64
	global_load_dwordx4 v[202:205], v20, s[58:59] offset:512
	global_load_dwordx4 v[206:209], v20, s[58:59] offset:576
	v_add_u32_e32 v20, 0x20000, v31
	global_load_dwordx4 v[210:213], v20, s[58:59]
	global_load_dwordx4 v[214:217], v20, s[58:59] offset:64
	global_load_dwordx4 v[218:221], v20, s[58:59] offset:512
	global_load_dwordx4 v[222:225], v20, s[58:59] offset:576
	v_add_u32_e32 v20, 0x30000, v31
	global_load_dwordx4 v[226:229], v20, s[58:59]
	global_load_dwordx4 v[232:235], v20, s[58:59] offset:64
	global_load_dwordx4 v[236:239], v20, s[58:59] offset:512
	global_load_dwordx4 v[240:243], v20, s[58:59] offset:576
	v_mov_b32_e32 v252, 0x358637bd
	v_mov_b32_e32 v250, v246
	v_not_b32_e32 v246, 31
	v_mov_b32_e32 v251, 0x7fc00000
	s_waitcnt vmcnt(0)
	v_mov_b32_e32 v20, v31
	v_add_u32_e32 v21, 0x80000, v31
	v_pk_fma_f32 v[134:135], v[134:135], v[26:27], v[150:151]
	v_pk_fma_f32 v[136:137], v[136:137], v[28:29], v[152:153]
	global_store_dwordx4 v20, v[134:137], s[58:59]
	global_load_dwordx4 v[150:153], v21, s[58:59]
	v_pk_fma_f32 v[22:23], v[22:23], v[138:139], v[154:155]
	v_pk_fma_f32 v[24:25], v[24:25], v[140:141], v[156:157]
	global_store_dwordx4 v20, v[22:25], s[58:59] offset:64
	global_load_dwordx4 v[154:157], v21, s[58:59] offset:64
	v_pk_fma_f32 v[4:5], v[4:5], v[142:143], v[164:165]
	v_pk_fma_f32 v[6:7], v[6:7], v[144:145], v[166:167]
	global_store_dwordx4 v20, v[4:7], s[58:59] offset:512
	global_load_dwordx4 v[164:167], v21, s[58:59] offset:512
	v_pk_fma_f32 v[130:131], v[130:131], v[146:147], v[168:169]
	v_pk_fma_f32 v[132:133], v[132:133], v[148:149], v[170:171]
	global_store_dwordx4 v20, v[130:133], s[58:59] offset:576
	global_load_dwordx4 v[168:171], v21, s[58:59] offset:576
	v_add_u32_e32 v20, 0x10000, v31
	v_add_u32_e32 v21, 0x90000, v31
	v_pk_fma_f32 v[126:127], v[126:127], v[26:27], v[172:173]
	v_pk_fma_f32 v[128:129], v[128:129], v[28:29], v[174:175]
	global_store_dwordx4 v20, v[126:129], s[58:59]
	global_load_dwordx4 v[172:175], v21, s[58:59]
	v_pk_fma_f32 v[118:119], v[118:119], v[138:139], v[198:199]
	v_pk_fma_f32 v[120:121], v[120:121], v[140:141], v[200:201]
	global_store_dwordx4 v20, v[118:121], s[58:59] offset:64
	global_load_dwordx4 v[198:201], v21, s[58:59] offset:64
	v_pk_fma_f32 v[122:123], v[122:123], v[142:143], v[202:203]
	v_pk_fma_f32 v[124:125], v[124:125], v[144:145], v[204:205]
	global_store_dwordx4 v20, v[122:125], s[58:59] offset:512
	global_load_dwordx4 v[202:205], v21, s[58:59] offset:512
	v_pk_fma_f32 v[114:115], v[114:115], v[146:147], v[206:207]
	v_pk_fma_f32 v[116:117], v[116:117], v[148:149], v[208:209]
	global_store_dwordx4 v20, v[114:117], s[58:59] offset:576
	global_load_dwordx4 v[206:209], v21, s[58:59] offset:576
	v_add_u32_e32 v20, 0x20000, v31
	v_add_u32_e32 v21, 0xa0000, v31
	v_pk_fma_f32 v[98:99], v[98:99], v[26:27], v[210:211]
	v_pk_fma_f32 v[100:101], v[100:101], v[28:29], v[212:213]
	global_store_dwordx4 v20, v[98:101], s[58:59]
	global_load_dwordx4 v[210:213], v21, s[58:59]
	v_pk_fma_f32 v[102:103], v[102:103], v[138:139], v[214:215]
	v_pk_fma_f32 v[104:105], v[104:105], v[140:141], v[216:217]
	global_store_dwordx4 v20, v[102:105], s[58:59] offset:64
	global_load_dwordx4 v[214:217], v21, s[58:59] offset:64
	v_pk_fma_f32 v[106:107], v[106:107], v[142:143], v[218:219]
	v_pk_fma_f32 v[108:109], v[108:109], v[144:145], v[220:221]
	global_store_dwordx4 v20, v[106:109], s[58:59] offset:512
	global_load_dwordx4 v[218:221], v21, s[58:59] offset:512
	v_pk_fma_f32 v[110:111], v[110:111], v[146:147], v[222:223]
	v_pk_fma_f32 v[112:113], v[112:113], v[148:149], v[224:225]
	global_store_dwordx4 v20, v[110:113], s[58:59] offset:576
	global_load_dwordx4 v[222:225], v21, s[58:59] offset:576
	v_add_u32_e32 v20, 0x30000, v31
	v_add_u32_e32 v21, 0xb0000, v31
	v_pk_fma_f32 v[84:85], v[84:85], v[26:27], v[226:227]
	v_pk_fma_f32 v[86:87], v[86:87], v[28:29], v[228:229]
	global_store_dwordx4 v20, v[84:87], s[58:59]
	global_load_dwordx4 v[226:229], v21, s[58:59]
	v_pk_fma_f32 v[80:81], v[80:81], v[138:139], v[232:233]
	v_pk_fma_f32 v[82:83], v[82:83], v[140:141], v[234:235]
	global_store_dwordx4 v20, v[80:83], s[58:59] offset:64
	global_load_dwordx4 v[232:235], v21, s[58:59] offset:64
	v_pk_fma_f32 v[92:93], v[92:93], v[142:143], v[236:237]
	v_pk_fma_f32 v[94:95], v[94:95], v[144:145], v[238:239]
	global_store_dwordx4 v20, v[92:95], s[58:59] offset:512
	global_load_dwordx4 v[236:239], v21, s[58:59] offset:512
	v_pk_fma_f32 v[88:89], v[88:89], v[146:147], v[240:241]
	v_pk_fma_f32 v[90:91], v[90:91], v[148:149], v[242:243]
	global_store_dwordx4 v20, v[88:91], s[58:59] offset:576
	global_load_dwordx4 v[240:243], v21, s[58:59] offset:576
	v_add_u32_e32 v21, 0x80000, v31
	s_waitcnt vmcnt(30)
	v_pk_fma_f32 v[68:69], v[68:69], v[26:27], v[150:151]
	v_pk_fma_f32 v[70:71], v[70:71], v[28:29], v[152:153]
	global_store_dwordx4 v21, v[68:71], s[58:59]
	s_waitcnt vmcnt(29)
	v_pk_fma_f32 v[64:65], v[64:65], v[138:139], v[154:155]
	v_pk_fma_f32 v[66:67], v[66:67], v[140:141], v[156:157]
	global_store_dwordx4 v21, v[64:67], s[58:59] offset:64
	s_waitcnt vmcnt(28)
	v_pk_fma_f32 v[76:77], v[76:77], v[142:143], v[164:165]
	v_pk_fma_f32 v[78:79], v[78:79], v[144:145], v[166:167]
	global_store_dwordx4 v21, v[76:79], s[58:59] offset:512
	s_waitcnt vmcnt(27)
	v_pk_fma_f32 v[72:73], v[72:73], v[146:147], v[168:169]
	v_pk_fma_f32 v[74:75], v[74:75], v[148:149], v[170:171]
	global_store_dwordx4 v21, v[72:75], s[58:59] offset:576
	v_add_u32_e32 v21, 0x90000, v31
	s_waitcnt vmcnt(26)
	v_pk_fma_f32 v[52:53], v[52:53], v[26:27], v[172:173]
	v_pk_fma_f32 v[54:55], v[54:55], v[28:29], v[174:175]
	global_store_dwordx4 v21, v[52:55], s[58:59]
	s_waitcnt vmcnt(25)
	v_pk_fma_f32 v[48:49], v[48:49], v[138:139], v[198:199]
	v_pk_fma_f32 v[50:51], v[50:51], v[140:141], v[200:201]
	global_store_dwordx4 v21, v[48:51], s[58:59] offset:64
	s_waitcnt vmcnt(24)
	v_pk_fma_f32 v[60:61], v[60:61], v[142:143], v[202:203]
	v_pk_fma_f32 v[62:63], v[62:63], v[144:145], v[204:205]
	global_store_dwordx4 v21, v[60:63], s[58:59] offset:512
	s_waitcnt vmcnt(23)
	v_pk_fma_f32 v[56:57], v[56:57], v[146:147], v[206:207]
	v_pk_fma_f32 v[58:59], v[58:59], v[148:149], v[208:209]
	global_store_dwordx4 v21, v[56:59], s[58:59] offset:576
	v_add_u32_e32 v21, 0xa0000, v31
	s_waitcnt vmcnt(22)
	v_pk_fma_f32 v[44:45], v[44:45], v[26:27], v[210:211]
	v_pk_fma_f32 v[46:47], v[46:47], v[28:29], v[212:213]
	global_store_dwordx4 v21, v[44:47], s[58:59]
	s_waitcnt vmcnt(21)
	v_pk_fma_f32 v[40:41], v[40:41], v[138:139], v[214:215]
	v_pk_fma_f32 v[42:43], v[42:43], v[140:141], v[216:217]
	global_store_dwordx4 v21, v[40:43], s[58:59] offset:64
	s_waitcnt vmcnt(20)
	v_pk_fma_f32 v[36:37], v[36:37], v[142:143], v[218:219]
	v_pk_fma_f32 v[38:39], v[38:39], v[144:145], v[220:221]
	global_store_dwordx4 v21, v[36:39], s[58:59] offset:512
	s_waitcnt vmcnt(19)
	v_pk_fma_f32 v[32:33], v[32:33], v[146:147], v[222:223]
	v_pk_fma_f32 v[34:35], v[34:35], v[148:149], v[224:225]
	global_store_dwordx4 v21, v[32:35], s[58:59] offset:576
	v_add_u32_e32 v21, 0xb0000, v31
	s_waitcnt vmcnt(18)
	v_pk_fma_f32 v[16:17], v[16:17], v[26:27], v[226:227]
	v_pk_fma_f32 v[18:19], v[18:19], v[28:29], v[228:229]
	global_store_dwordx4 v21, v[16:19], s[58:59]
	s_waitcnt vmcnt(17)
	v_pk_fma_f32 v[12:13], v[12:13], v[138:139], v[232:233]
	v_pk_fma_f32 v[14:15], v[14:15], v[140:141], v[234:235]
	global_store_dwordx4 v21, v[12:15], s[58:59] offset:64
	s_waitcnt vmcnt(16)
	v_pk_fma_f32 v[8:9], v[8:9], v[142:143], v[236:237]
	v_pk_fma_f32 v[10:11], v[10:11], v[144:145], v[238:239]
	global_store_dwordx4 v21, v[8:11], s[58:59] offset:512
	s_waitcnt vmcnt(15)
	v_pk_fma_f32 v[0:1], v[0:1], v[146:147], v[240:241]
	v_pk_fma_f32 v[2:3], v[2:3], v[148:149], v[242:243]
	global_store_dwordx4 v21, v[0:3], s[58:59] offset:576
	s_load_dwordx2 s[98:99], s[54:55], 0x30
	s_add_u32 s28, s0, 0x1000
	s_addc_u32 s29, s1, 0
	s_add_u32 s50, s0, 0x2000
	s_addc_u32 s51, s1, 0
	s_waitcnt lgkmcnt(0)
	s_add_u32 s98, s98, 0x3000
	s_addc_u32 s99, s99, 0
	global_load_dwordx4 v[150:153], v30, s[50:51]
	global_load_dwordx4 v[154:157], v30, s[50:51] offset:64
	global_load_dwordx4 v[164:167], v30, s[50:51] offset:512
	global_load_dwordx4 v[168:171], v30, s[50:51] offset:576
	global_load_dwordx4 v[210:213], v30, s[98:99]
	global_load_dwordx4 v[214:217], v30, s[98:99] offset:64
	global_load_dwordx4 v[218:221], v30, s[98:99] offset:512
	global_load_dwordx4 v[222:225], v30, s[98:99] offset:576
	global_load_dwordx4 v[172:175], v30, s[28:29]
	global_load_dwordx4 v[198:201], v30, s[28:29] offset:64
	global_load_dwordx4 v[202:205], v30, s[28:29] offset:512
	global_load_dwordx4 v[206:209], v30, s[28:29] offset:576
	v_pk_mul_f32 v[26:27], v[134:135], v[134:135]
	v_pk_mul_f32 v[28:29], v[126:127], v[126:127]
	v_pk_fma_f32 v[26:27], v[136:137], v[136:137], v[26:27]
	v_pk_fma_f32 v[28:29], v[128:129], v[128:129], v[28:29]
	v_pk_fma_f32 v[26:27], v[22:23], v[22:23], v[26:27]
	v_pk_fma_f32 v[28:29], v[118:119], v[118:119], v[28:29]
	v_pk_fma_f32 v[26:27], v[24:25], v[24:25], v[26:27]
	v_pk_fma_f32 v[28:29], v[120:121], v[120:121], v[28:29]
	v_pk_fma_f32 v[26:27], v[4:5], v[4:5], v[26:27]
	v_pk_fma_f32 v[28:29], v[122:123], v[122:123], v[28:29]
	v_pk_fma_f32 v[26:27], v[6:7], v[6:7], v[26:27]
	v_pk_fma_f32 v[28:29], v[124:125], v[124:125], v[28:29]
	v_pk_fma_f32 v[26:27], v[130:131], v[130:131], v[26:27]
	v_pk_fma_f32 v[28:29], v[114:115], v[114:115], v[28:29]
	v_pk_fma_f32 v[26:27], v[132:133], v[132:133], v[26:27]
	v_pk_fma_f32 v[28:29], v[116:117], v[116:117], v[28:29]
	s_nop 0
	v_add_f32_e32 v138, v26, v27
	v_add_f32_e32 v139, v28, v29
	v_pk_mul_f32 v[26:27], v[98:99], v[98:99]
	v_pk_mul_f32 v[28:29], v[84:85], v[84:85]
	v_pk_fma_f32 v[26:27], v[100:101], v[100:101], v[26:27]
	v_pk_fma_f32 v[28:29], v[86:87], v[86:87], v[28:29]
	v_pk_fma_f32 v[26:27], v[102:103], v[102:103], v[26:27]
	v_pk_fma_f32 v[28:29], v[80:81], v[80:81], v[28:29]
	v_pk_fma_f32 v[26:27], v[104:105], v[104:105], v[26:27]
	v_pk_fma_f32 v[28:29], v[82:83], v[82:83], v[28:29]
	v_pk_fma_f32 v[26:27], v[106:107], v[106:107], v[26:27]
	v_pk_fma_f32 v[28:29], v[92:93], v[92:93], v[28:29]
	v_pk_fma_f32 v[26:27], v[108:109], v[108:109], v[26:27]
	v_pk_fma_f32 v[28:29], v[94:95], v[94:95], v[28:29]
	v_pk_fma_f32 v[26:27], v[110:111], v[110:111], v[26:27]
	v_pk_fma_f32 v[28:29], v[88:89], v[88:89], v[28:29]
	v_pk_fma_f32 v[26:27], v[112:113], v[112:113], v[26:27]
	v_pk_fma_f32 v[28:29], v[90:91], v[90:91], v[28:29]
	s_nop 0
	v_add_f32_e32 v140, v26, v27
	v_add_f32_e32 v141, v28, v29
	v_pk_mul_f32 v[26:27], v[68:69], v[68:69]
	v_pk_mul_f32 v[28:29], v[52:53], v[52:53]
	v_pk_fma_f32 v[26:27], v[70:71], v[70:71], v[26:27]
	v_pk_fma_f32 v[28:29], v[54:55], v[54:55], v[28:29]
	v_pk_fma_f32 v[26:27], v[64:65], v[64:65], v[26:27]
	v_pk_fma_f32 v[28:29], v[48:49], v[48:49], v[28:29]
	v_pk_fma_f32 v[26:27], v[66:67], v[66:67], v[26:27]
	v_pk_fma_f32 v[28:29], v[50:51], v[50:51], v[28:29]
	v_pk_fma_f32 v[26:27], v[76:77], v[76:77], v[26:27]
	v_pk_fma_f32 v[28:29], v[60:61], v[60:61], v[28:29]
	v_pk_fma_f32 v[26:27], v[78:79], v[78:79], v[26:27]
	v_pk_fma_f32 v[28:29], v[62:63], v[62:63], v[28:29]
	v_pk_fma_f32 v[26:27], v[72:73], v[72:73], v[26:27]
	v_pk_fma_f32 v[28:29], v[56:57], v[56:57], v[28:29]
	v_pk_fma_f32 v[26:27], v[74:75], v[74:75], v[26:27]
	v_pk_fma_f32 v[28:29], v[58:59], v[58:59], v[28:29]
	s_nop 0
	v_add_f32_e32 v142, v26, v27
	v_add_f32_e32 v143, v28, v29
	v_pk_mul_f32 v[26:27], v[44:45], v[44:45]
	v_pk_mul_f32 v[28:29], v[16:17], v[16:17]
	v_pk_fma_f32 v[26:27], v[46:47], v[46:47], v[26:27]
	v_pk_fma_f32 v[28:29], v[18:19], v[18:19], v[28:29]
	v_pk_fma_f32 v[26:27], v[40:41], v[40:41], v[26:27]
	v_pk_fma_f32 v[28:29], v[12:13], v[12:13], v[28:29]
	v_pk_fma_f32 v[26:27], v[42:43], v[42:43], v[26:27]
	v_pk_fma_f32 v[28:29], v[14:15], v[14:15], v[28:29]
	v_pk_fma_f32 v[26:27], v[36:37], v[36:37], v[26:27]
	v_pk_fma_f32 v[28:29], v[8:9], v[8:9], v[28:29]
	v_pk_fma_f32 v[26:27], v[38:39], v[38:39], v[26:27]
	v_pk_fma_f32 v[28:29], v[10:11], v[10:11], v[28:29]
	v_pk_fma_f32 v[26:27], v[32:33], v[32:33], v[26:27]
	v_pk_fma_f32 v[28:29], v[0:1], v[0:1], v[28:29]
	v_pk_fma_f32 v[26:27], v[34:35], v[34:35], v[26:27]
	v_pk_fma_f32 v[28:29], v[2:3], v[2:3], v[28:29]
	s_nop 0
	v_add_f32_e32 v144, v26, v27
	v_add_f32_e32 v145, v28, v29
	s_barrier
	ds_write_b32 v96, v138
	ds_write_b32 v96, v139 offset:1024
	ds_write_b32 v96, v140 offset:2048
	ds_write_b32 v96, v141 offset:3072
	ds_write_b32 v96, v142 offset:8192
	ds_write_b32 v96, v143 offset:9216
	ds_write_b32 v96, v144 offset:10240
	ds_write_b32 v96, v145 offset:11264
	s_lshr_b32 s30, s6, 8
	s_lshl_b32 s30, s30, 2
	s_lshl_b32 s3, s4, 8
	s_add_u32 s4, s46, s30
	s_addc_u32 s5, s47, 0
	s_add_u32 s4, s4, 0xdacc200
	s_addc_u32 s5, s5, 0
	s_lshl_b32 s30, s6, 2
	s_add_u32 s0, s44, s30
	s_addc_u32 s1, s45, 0
	s_add_u32 s0, s0, 0x2200000
	s_addc_u32 s1, s1, 0
	s_waitcnt lgkmcnt(0)
	s_barrier
	s_cmp_ge_u32 s48, 0x100
	s_cbranch_scc1 .Lfu_norow
	v_mbcnt_lo_u32_b32 v158, -1, 0
	v_mbcnt_hi_u32_b32 v158, -1, v158
	v_add_u32_e32 v158, s48, v158
	v_lshlrev_b32_e32 v159, 6, v158
	ds_read_b128 v[226:229], v159
	ds_read_b128 v[232:235], v159 offset:16
	ds_read_b128 v[236:239], v159 offset:32
	ds_read_b128 v[240:243], v159 offset:48
	v_lshlrev_b32_e32 v158, 2, v158
	s_waitcnt lgkmcnt(0)
	v_add_u32_e32 v159, s3, v158
	v_pk_add_f32 v[226:227], v[226:227], v[228:229]
	v_pk_add_f32 v[232:233], v[232:233], v[234:235]
	v_pk_add_f32 v[236:237], v[236:237], v[238:239]
	v_pk_add_f32 v[240:241], v[240:241], v[242:243]
	v_pk_add_f32 v[226:227], v[226:227], v[232:233]
	v_pk_add_f32 v[236:237], v[236:237], v[240:241]
	s_nop 0
	v_pk_add_f32 v[226:227], v[226:227], v[236:237]
	s_nop 0
	v_add_f32_e32 v160, v226, v227
	s_nop 0
	global_store_dword v159, v160, s[0:1] sc0 sc1
.Lfu_norow:
	s_waitcnt vmcnt(0)
	s_barrier
	v_pk_add_f32 v[150:151], v[150:151], 1.0 op_sel_hi:[1,0]
	v_pk_add_f32 v[152:153], v[152:153], 1.0 op_sel_hi:[1,0]
	v_pk_add_f32 v[154:155], v[154:155], 1.0 op_sel_hi:[1,0]
	v_pk_add_f32 v[156:157], v[156:157], 1.0 op_sel_hi:[1,0]
	v_pk_add_f32 v[164:165], v[164:165], 1.0 op_sel_hi:[1,0]
	v_pk_add_f32 v[166:167], v[166:167], 1.0 op_sel_hi:[1,0]
	v_pk_add_f32 v[168:169], v[168:169], 1.0 op_sel_hi:[1,0]
	v_pk_add_f32 v[170:171], v[170:171], 1.0 op_sel_hi:[1,0]
	v_pk_mul_f32 v[150:151], v[210:211], v[150:151]
	v_pk_mul_f32 v[152:153], v[212:213], v[152:153]
	v_pk_mul_f32 v[154:155], v[214:215], v[154:155]
	v_pk_mul_f32 v[156:157], v[216:217], v[156:157]
	v_pk_mul_f32 v[164:165], v[218:219], v[164:165]
	v_pk_mul_f32 v[166:167], v[220:221], v[166:167]
	v_pk_mul_f32 v[168:169], v[222:223], v[168:169]
	v_pk_mul_f32 v[170:171], v[224:225], v[170:171]
	s_cmp_lg_u32 s48, 0
	s_cbranch_scc1 .Lfu_nosig
	v_mov_b32_e32 v244, 0
	v_mov_b32_e32 v245, 1
	s_mov_b64 exec, 1
	global_atomic_add v244, v245, s[4:5]
	s_mov_b64 exec, -1
	s_mov_b32 s32, 0
.Lfu_spin:
	global_load_dword v245, v244, s[4:5] sc1
	s_add_i32 s32, s32, 1
	s_waitcnt vmcnt(0)
	v_readfirstlane_b32 s30, v245
	s_cmp_ge_u32 s30, 4
	s_cbranch_scc1 .Lfu_nosig
	s_cmp_gt_u32 s32, 0x40000
	s_cbranch_scc1 .Lfu_nosig
	s_sleep 4
	s_branch .Lfu_spin
.Lfu_nosig:
	s_barrier
	s_cmp_ge_u32 s48, 0x100
	s_cbranch_scc1 .Lfu_norow2
	global_load_dword v226, v158, s[0:1] sc0 sc1
	v_add_u32_e32 v159, 0x10000, v158
	global_load_dword v227, v159, s[0:1] sc0 sc1
	v_add_u32_e32 v159, 0x20000, v158
	global_load_dword v228, v159, s[0:1] sc0 sc1
	v_add_u32_e32 v159, 0x30000, v158
	global_load_dword v229, v159, s[0:1] sc0 sc1
	v_mov_b32_e32 v232, 0x3a800000
	s_waitcnt vmcnt(0)
	v_add_f32_e32 v226, v226, v227
	s_nop 0
	v_add_f32_e32 v226, v226, v228
	s_nop 0
	v_add_f32_e32 v226, v226, v229
	s_nop 0
	v_fma_f32 v226, v226, v232, v252
	s_nop 0
	v_mul_f32_e32 v227, 0x4b800000, v226
	v_cmp_gt_f32_e32 vcc, s84, v226
	s_nop 1
	v_cndmask_b32_e32 v226, v226, v227, vcc
	s_nop 0
	v_rsq_f32_e32 v226, v226
	s_nop 1
	v_mul_f32_e32 v227, 0x45800000, v226
	s_nop 0
	v_cndmask_b32_e32 v226, v226, v227, vcc
	s_nop 0
	ds_write_b32 v158, v226 offset:16384
